# A epilogue: relax redundant vmcnt(0) drains (sample-tile cvv waits count only loads; q/k per-group gv waits)
# speedup vs baseline: 1.0063x; 1.0016x over previous
.LBB0_433:
	s_ashr_i32 s8, s5, 4
	s_or_b32 s8, s8, 3
	s_mul_hi_i32 s9, s8, 0x4800
	s_mulk_i32 s8, 0x4800
	s_add_u32 s8, s79, s8
	s_addc_u32 s9, s80, s9
	s_waitcnt vmcnt(12)
	v_lshl_add_u64 v[160:161], v[202:203], 2, s[8:9]
	global_load_dwordx4 v[152:155], v[160:161], off offset:16
	global_load_dwordx4 v[148:151], v[160:161], off
	global_load_dwordx4 v[156:159], v[160:161], off offset:528
	s_nop 0
	global_load_dwordx4 v[160:163], v[160:161], off offset:512

.LBB0_453:
	s_ashr_i32 s4, s5, 4
	s_add_i32 s4, s4, 4
	s_mul_hi_i32 s11, s4, 0x4800
	s_mulk_i32 s4, 0x4800
	s_add_u32 s10, s79, s4
	s_addc_u32 s11, s80, s11
	s_waitcnt vmcnt(12)
	v_lshl_add_u64 v[160:161], v[202:203], 2, s[10:11]
	global_load_dwordx4 v[152:155], v[160:161], off offset:16
	global_load_dwordx4 v[148:151], v[160:161], off
	global_load_dwordx4 v[156:159], v[160:161], off offset:528
	s_nop 0
	global_load_dwordx4 v[160:163], v[160:161], off offset:512

.LBB0_464:
	s_andn2_b64 vcc, exec, s[10:11]
	s_cbranch_vccnz .LBB0_470
	s_andn2_b64 vcc, exec, s[76:77]
	s_cbranch_vccnz .LBB0_467
	v_pk_mul_f32 v[218:219], v[178:179], v[178:179]
	v_pk_mul_f32 v[220:221], v[176:177], v[176:177]
	s_nop 0
	v_pk_mov_b32 v[222:223], v[220:221], v[218:219] op_sel:[1,0]
	v_mov_b32_e32 v221, v219
	v_pk_add_f32 v[218:219], v[222:223], v[220:221]
	v_pk_mul_f32 v[220:221], v[166:167], v[166:167]
	v_pk_add_f32 v[218:219], v[218:219], v[218:219] op_sel_hi:[0,1]
	v_pk_mul_f32 v[222:223], v[164:165], v[164:165]
	v_mul_f32_e32 v218, v168, v168
	v_pk_mov_b32 v[224:225], v[222:223], v[220:221] op_sel:[1,0]
	v_mov_b32_e32 v223, v221
	v_pk_add_f32 v[220:221], v[224:225], v[222:223]
	v_pk_fma_f32 v[222:223], v[168:169], v[168:169], v[218:219] op_sel_hi:[1,1,0]
	v_mul_f32_e32 v218, v170, v170
	v_pk_add_f32 v[220:221], v[220:221], v[220:221] op_sel_hi:[0,1]
	v_pk_fma_f32 v[224:225], v[170:171], v[170:171], v[218:219] op_sel_hi:[1,1,0]
	v_mul_f32_e32 v222, v172, v172
	v_mul_f32_e32 v224, v173, v173
	v_mul_f32_e32 v220, v174, v174
	v_mul_f32_e32 v218, v175, v175
	v_pk_add_f32 v[222:223], v[222:223], v[224:225]
	v_pk_add_f32 v[218:219], v[220:221], v[218:219]
	s_nop 0
	v_pk_add_f32 v[218:219], v[222:223], v[218:219]
	s_nop 0
	v_add_f32_e32 v217, v218, v219
	ds_bpermute_b32 v218, v208, v217
	s_waitcnt lgkmcnt(0)
	v_add_f32_e32 v217, v217, v218
	ds_bpermute_b32 v218, v209, v217
	s_waitcnt lgkmcnt(0)
	v_add_f32_e32 v217, v217, v218
	v_fmamk_f32 v217, v217, 0x3c800000, v229
	v_rsq_f32_e32 v218, v217
	s_nop 0
	v_pk_mul_f32 v[176:177], v[176:177], v[218:219] op_sel_hi:[1,0]
	v_pk_mul_f32 v[178:179], v[178:179], v[218:219] op_sel_hi:[1,0]
	v_pk_mul_f32 v[164:165], v[164:165], v[218:219] op_sel_hi:[1,0]
	v_pk_mul_f32 v[166:167], v[166:167], v[218:219] op_sel_hi:[1,0]
	v_pk_mul_f32 v[168:169], v[168:169], v[218:219] op_sel_hi:[1,0]
	v_pk_mul_f32 v[170:171], v[170:171], v[218:219] op_sel_hi:[1,0]
	v_pk_mul_f32 v[172:173], v[172:173], v[218:219] op_sel_hi:[1,0]
	v_pk_mul_f32 v[174:175], v[174:175], v[218:219] op_sel_hi:[1,0]
	s_waitcnt vmcnt(12)
	v_pk_mul_f32 v[178:179], v[146:147], v[178:179]
	v_pk_mul_f32 v[176:177], v[144:145], v[176:177]
	v_pk_mul_f32 v[166:167], v[142:143], v[166:167]
	v_pk_mul_f32 v[164:165], v[140:141], v[164:165]
	v_pk_mul_f32 v[170:171], v[138:139], v[170:171]
	v_pk_mul_f32 v[168:169], v[136:137], v[168:169]
	v_pk_mul_f32 v[174:175], v[134:135], v[174:175]
	v_pk_mul_f32 v[172:173], v[132:133], v[172:173]

.LBB0_473:
	s_ashr_i32 s4, s5, 4
	s_add_i32 s4, s4, 5
	s_mul_hi_i32 s5, s4, 0x4800
	s_mulk_i32 s4, 0x4800
	s_add_u32 s4, s79, s4
	s_addc_u32 s5, s80, s5
	s_waitcnt vmcnt(12)
	v_lshl_add_u64 v[160:161], v[202:203], 2, s[4:5]
	global_load_dwordx4 v[152:155], v[160:161], off offset:16
	global_load_dwordx4 v[148:151], v[160:161], off
	global_load_dwordx4 v[156:159], v[160:161], off offset:528
	s_nop 0
	global_load_dwordx4 v[160:163], v[160:161], off offset:512

.LBB0_493:
	s_add_i32 s4, s53, 0xffffc080
	s_ashr_i32 s4, s4, 4
	s_or_b32 s4, s4, 2
	s_mul_hi_i32 s5, s4, 0x4800
	s_mulk_i32 s4, 0x4800
	s_add_u32 s4, s79, s4
	s_addc_u32 s5, s80, s5
	s_waitcnt vmcnt(12)
	v_lshl_add_u64 v[160:161], v[202:203], 2, s[4:5]
	global_load_dwordx4 v[152:155], v[160:161], off offset:16
	global_load_dwordx4 v[148:151], v[160:161], off
	global_load_dwordx4 v[156:159], v[160:161], off offset:528
	s_nop 0
	global_load_dwordx4 v[160:163], v[160:161], off offset:512

.LBB0_513:
	s_add_i32 s4, s53, 0xffffc090
	s_ashr_i32 s4, s4, 4
	s_or_b32 s4, s4, 2
	s_mul_hi_i32 s5, s4, 0x4800
	s_mulk_i32 s4, 0x4800
	s_add_u32 s4, s79, s4
	s_addc_u32 s5, s80, s5
	s_waitcnt vmcnt(12)
	v_lshl_add_u64 v[160:161], v[202:203], 2, s[4:5]
	global_load_dwordx4 v[152:155], v[160:161], off offset:16
	global_load_dwordx4 v[148:151], v[160:161], off
	global_load_dwordx4 v[156:159], v[160:161], off offset:528
	s_nop 0
	global_load_dwordx4 v[160:163], v[160:161], off offset:512

.LBB0_533:
	s_add_i32 s4, s53, 0xffffc0a0
	s_ashr_i32 s4, s4, 4
	s_add_i32 s4, s4, 2
	s_mul_hi_i32 s5, s4, 0x4800
	s_mulk_i32 s4, 0x4800
	s_add_u32 s4, s79, s4
	s_addc_u32 s5, s80, s5
	s_waitcnt vmcnt(12)
	v_lshl_add_u64 v[160:161], v[202:203], 2, s[4:5]
	global_load_dwordx4 v[152:155], v[160:161], off offset:16
	global_load_dwordx4 v[148:151], v[160:161], off
	global_load_dwordx4 v[156:159], v[160:161], off offset:528
	s_nop 0
	global_load_dwordx4 v[160:163], v[160:161], off offset:512

.LBB0_553:
	s_addk_i32 s53, 0xc0b0
	s_ashr_i32 s4, s53, 4
	s_add_i32 s4, s4, 2
	s_mul_hi_i32 s5, s4, 0x4800
	s_mulk_i32 s4, 0x4800
	s_add_u32 s4, s79, s4
	s_addc_u32 s5, s80, s5
	s_waitcnt vmcnt(12)
	v_lshl_add_u64 v[160:161], v[202:203], 2, s[4:5]
	global_load_dwordx4 v[152:155], v[160:161], off offset:16
	global_load_dwordx4 v[148:151], v[160:161], off
	global_load_dwordx4 v[156:159], v[160:161], off offset:528
	s_nop 0
	global_load_dwordx4 v[160:163], v[160:161], off offset:512

.LBB0_564:
	s_andn2_b64 vcc, exec, s[10:11]
	s_cbranch_vccnz .LBB0_570
	s_andn2_b64 vcc, exec, s[76:77]
	s_cbranch_vccnz .LBB0_567
	v_pk_mul_f32 v[204:205], v[178:179], v[178:179]
	v_pk_mul_f32 v[218:219], v[176:177], v[176:177]
	s_nop 0
	v_pk_mov_b32 v[220:221], v[218:219], v[204:205] op_sel:[1,0]
	v_mov_b32_e32 v219, v205
	v_pk_add_f32 v[204:205], v[220:221], v[218:219]
	v_pk_mul_f32 v[218:219], v[166:167], v[166:167]
	v_pk_add_f32 v[204:205], v[204:205], v[204:205] op_sel_hi:[0,1]
	v_pk_mul_f32 v[220:221], v[164:165], v[164:165]
	v_mul_f32_e32 v204, v168, v168
	v_pk_mov_b32 v[222:223], v[220:221], v[218:219] op_sel:[1,0]
	v_mov_b32_e32 v221, v219
	v_pk_add_f32 v[218:219], v[222:223], v[220:221]
	v_pk_fma_f32 v[220:221], v[168:169], v[168:169], v[204:205] op_sel_hi:[1,1,0]
	v_mul_f32_e32 v204, v170, v170
	v_pk_add_f32 v[218:219], v[218:219], v[218:219] op_sel_hi:[0,1]
	v_pk_fma_f32 v[222:223], v[170:171], v[170:171], v[204:205] op_sel_hi:[1,1,0]
	v_mul_f32_e32 v220, v172, v172
	v_mul_f32_e32 v222, v173, v173
	v_mul_f32_e32 v218, v174, v174
	v_mul_f32_e32 v204, v175, v175
	v_pk_add_f32 v[220:221], v[220:221], v[222:223]
	v_pk_add_f32 v[204:205], v[218:219], v[204:205]
	s_nop 0
	v_pk_add_f32 v[204:205], v[220:221], v[204:205]
	s_nop 0
	v_add_f32_e32 v204, v204, v205
	ds_bpermute_b32 v205, v208, v204
	s_waitcnt lgkmcnt(0)
	v_add_f32_e32 v204, v204, v205
	ds_bpermute_b32 v205, v209, v204
	s_waitcnt lgkmcnt(0)
	v_add_f32_e32 v204, v204, v205
	v_fmamk_f32 v204, v204, 0x3c800000, v229
	v_rsq_f32_e32 v204, v204
	s_nop 0
	v_pk_mul_f32 v[176:177], v[176:177], v[204:205] op_sel_hi:[1,0]
	v_pk_mul_f32 v[178:179], v[178:179], v[204:205] op_sel_hi:[1,0]
	v_pk_mul_f32 v[164:165], v[164:165], v[204:205] op_sel_hi:[1,0]
	v_pk_mul_f32 v[166:167], v[166:167], v[204:205] op_sel_hi:[1,0]
	v_pk_mul_f32 v[168:169], v[168:169], v[204:205] op_sel_hi:[1,0]
	v_pk_mul_f32 v[170:171], v[170:171], v[204:205] op_sel_hi:[1,0]
	v_pk_mul_f32 v[172:173], v[172:173], v[204:205] op_sel_hi:[1,0]
	v_pk_mul_f32 v[174:175], v[174:175], v[204:205] op_sel_hi:[1,0]
	s_waitcnt vmcnt(12)
	v_pk_mul_f32 v[178:179], v[146:147], v[178:179]
	v_pk_mul_f32 v[176:177], v[144:145], v[176:177]
	v_pk_mul_f32 v[166:167], v[142:143], v[166:167]
	v_pk_mul_f32 v[164:165], v[140:141], v[164:165]
	v_pk_mul_f32 v[170:171], v[138:139], v[170:171]
	v_pk_mul_f32 v[168:169], v[136:137], v[168:169]
	v_pk_mul_f32 v[174:175], v[134:135], v[174:175]
	v_pk_mul_f32 v[172:173], v[132:133], v[172:173]

.LBB0_595:
	v_mov_b32_e32 v174, v204
	v_mov_b32_e32 v175, v204
	v_mov_b32_e32 v172, v196
	v_mov_b32_e32 v173, v196
	v_pk_mul_f32 v[164:165], v[118:119], v[174:175]
	v_pk_mul_f32 v[168:169], v[116:117], v[204:205]
	s_waitcnt vmcnt(2)
	v_pk_fma_f32 v[166:167], v[172:173], v[154:155], v[164:165]
	v_pk_fma_f32 v[164:165], v[196:197], v[152:153], v[168:169]
	v_pk_mul_f32 v[168:169], v[90:91], v[174:175]
	v_pk_mul_f32 v[218:219], v[88:89], v[204:205]
	v_pk_fma_f32 v[170:171], v[172:173], v[162:163], v[168:169]
	v_pk_fma_f32 v[168:169], v[196:197], v[160:161], v[218:219]
	v_pk_mul_f32 v[174:175], v[86:87], v[174:175]
	v_pk_mul_f32 v[218:219], v[84:85], v[204:205]
	v_pk_mul_f32 v[178:179], v[172:173], v[150:151]
	v_pk_mul_f32 v[176:177], v[196:197], v[148:149]
	v_pk_fma_f32 v[174:175], v[172:173], v[158:159], v[174:175]
	v_pk_fma_f32 v[172:173], v[196:197], v[156:157], v[218:219]
	s_cbranch_execnz .LBB0_452
.LBB0_596:
	v_mov_b32_e32 v172, v204
	v_mov_b32_e32 v173, v204
	s_waitcnt vmcnt(2)
	v_mov_b64_e32 v[178:179], v[150:151]
	v_pk_fma_f32 v[166:167], v[118:119], v[172:173], v[154:155]
	v_pk_fma_f32 v[164:165], v[116:117], v[204:205], v[152:153]
	v_pk_fma_f32 v[170:171], v[90:91], v[172:173], v[162:163]
	v_pk_fma_f32 v[168:169], v[88:89], v[204:205], v[160:161]
	v_pk_fma_f32 v[174:175], v[86:87], v[172:173], v[158:159]
	v_pk_fma_f32 v[172:173], v[84:85], v[204:205], v[156:157]
	v_mov_b64_e32 v[176:177], v[148:149]
	s_and_b64 vcc, exec, s[40:41]
	s_cbranch_vccz .LBB0_453
	s_branch .LBB0_454
.LBB0_597:
	v_mov_b32_e32 v174, v204
	v_mov_b32_e32 v175, v204
	v_mov_b32_e32 v172, v196
	v_mov_b32_e32 v173, v196
	v_pk_mul_f32 v[164:165], v[110:111], v[174:175]
	v_pk_mul_f32 v[168:169], v[108:109], v[204:205]
	s_waitcnt vmcnt(2)
	v_pk_fma_f32 v[166:167], v[172:173], v[154:155], v[164:165]
	v_pk_fma_f32 v[164:165], v[196:197], v[152:153], v[168:169]
	v_pk_mul_f32 v[168:169], v[82:83], v[174:175]
	v_pk_mul_f32 v[218:219], v[80:81], v[204:205]
	v_pk_fma_f32 v[170:171], v[172:173], v[162:163], v[168:169]
	v_pk_fma_f32 v[168:169], v[196:197], v[160:161], v[218:219]
	v_pk_mul_f32 v[174:175], v[78:79], v[174:175]
	v_pk_mul_f32 v[218:219], v[76:77], v[204:205]
	v_pk_mul_f32 v[178:179], v[172:173], v[150:151]
	v_pk_mul_f32 v[176:177], v[196:197], v[148:149]
	v_pk_fma_f32 v[174:175], v[172:173], v[158:159], v[174:175]
	v_pk_fma_f32 v[172:173], v[196:197], v[156:157], v[218:219]
	s_cbranch_execnz .LBB0_472
.LBB0_598:
	v_mov_b32_e32 v172, v204
	v_mov_b32_e32 v173, v204
	s_waitcnt vmcnt(2)
	v_mov_b64_e32 v[178:179], v[150:151]
	v_pk_fma_f32 v[166:167], v[110:111], v[172:173], v[154:155]
	v_pk_fma_f32 v[164:165], v[108:109], v[204:205], v[152:153]
	v_pk_fma_f32 v[170:171], v[82:83], v[172:173], v[162:163]
	v_pk_fma_f32 v[168:169], v[80:81], v[204:205], v[160:161]
	v_pk_fma_f32 v[174:175], v[78:79], v[172:173], v[158:159]
	v_pk_fma_f32 v[172:173], v[76:77], v[204:205], v[156:157]
	v_mov_b64_e32 v[176:177], v[148:149]
	s_and_b64 vcc, exec, s[40:41]
	s_cbranch_vccz .LBB0_473
	s_branch .LBB0_474
.LBB0_599:
	v_mov_b32_e32 v174, v204
	v_mov_b32_e32 v175, v204
	v_mov_b32_e32 v172, v196
	v_mov_b32_e32 v173, v196
	v_pk_mul_f32 v[164:165], v[102:103], v[174:175]
	v_pk_mul_f32 v[168:169], v[100:101], v[204:205]
	s_waitcnt vmcnt(2)
	v_pk_fma_f32 v[166:167], v[172:173], v[154:155], v[164:165]
	v_pk_fma_f32 v[164:165], v[196:197], v[152:153], v[168:169]
	v_pk_mul_f32 v[168:169], v[74:75], v[174:175]
	v_pk_mul_f32 v[218:219], v[72:73], v[204:205]
	v_pk_fma_f32 v[170:171], v[172:173], v[162:163], v[168:169]
	v_pk_fma_f32 v[168:169], v[196:197], v[160:161], v[218:219]
	v_pk_mul_f32 v[174:175], v[70:71], v[174:175]
	v_pk_mul_f32 v[218:219], v[68:69], v[204:205]
	v_pk_mul_f32 v[178:179], v[172:173], v[150:151]
	v_pk_mul_f32 v[176:177], v[196:197], v[148:149]
	v_pk_fma_f32 v[174:175], v[172:173], v[158:159], v[174:175]
	v_pk_fma_f32 v[172:173], v[196:197], v[156:157], v[218:219]
	s_cbranch_execnz .LBB0_492
.LBB0_600:
	v_mov_b32_e32 v172, v204
	v_mov_b32_e32 v173, v204
	s_waitcnt vmcnt(2)
	v_mov_b64_e32 v[178:179], v[150:151]
	v_pk_fma_f32 v[166:167], v[102:103], v[172:173], v[154:155]
	v_pk_fma_f32 v[164:165], v[100:101], v[204:205], v[152:153]
	v_pk_fma_f32 v[170:171], v[74:75], v[172:173], v[162:163]
	v_pk_fma_f32 v[168:169], v[72:73], v[204:205], v[160:161]
	v_pk_fma_f32 v[174:175], v[70:71], v[172:173], v[158:159]
	v_pk_fma_f32 v[172:173], v[68:69], v[204:205], v[156:157]
	v_mov_b64_e32 v[176:177], v[148:149]
	s_and_b64 vcc, exec, s[40:41]
	s_cbranch_vccz .LBB0_493
	s_branch .LBB0_494
.LBB0_601:
	v_mov_b32_e32 v174, v204
	v_mov_b32_e32 v175, v204
	v_mov_b32_e32 v172, v196
	v_mov_b32_e32 v173, v196
	v_pk_mul_f32 v[164:165], v[62:63], v[174:175]
	v_pk_mul_f32 v[168:169], v[60:61], v[204:205]
	s_waitcnt vmcnt(2)
	v_pk_fma_f32 v[166:167], v[172:173], v[154:155], v[164:165]
	v_pk_fma_f32 v[164:165], v[196:197], v[152:153], v[168:169]
	v_pk_mul_f32 v[168:169], v[34:35], v[174:175]
	v_pk_mul_f32 v[218:219], v[32:33], v[204:205]
	v_pk_fma_f32 v[170:171], v[172:173], v[162:163], v[168:169]
	v_pk_fma_f32 v[168:169], v[196:197], v[160:161], v[218:219]
	v_pk_mul_f32 v[174:175], v[30:31], v[174:175]
	v_pk_mul_f32 v[218:219], v[28:29], v[204:205]
	v_pk_mul_f32 v[178:179], v[172:173], v[150:151]
	v_pk_mul_f32 v[176:177], v[196:197], v[148:149]
	v_pk_fma_f32 v[174:175], v[172:173], v[158:159], v[174:175]
	v_pk_fma_f32 v[172:173], v[196:197], v[156:157], v[218:219]
	s_cbranch_execnz .LBB0_512
.LBB0_602:
	v_mov_b32_e32 v172, v204
	v_mov_b32_e32 v173, v204
	s_waitcnt vmcnt(2)
	v_mov_b64_e32 v[178:179], v[150:151]
	v_pk_fma_f32 v[166:167], v[62:63], v[172:173], v[154:155]
	v_pk_fma_f32 v[164:165], v[60:61], v[204:205], v[152:153]
	v_pk_fma_f32 v[170:171], v[34:35], v[172:173], v[162:163]
	v_pk_fma_f32 v[168:169], v[32:33], v[204:205], v[160:161]
	v_pk_fma_f32 v[174:175], v[30:31], v[172:173], v[158:159]
	v_pk_fma_f32 v[172:173], v[28:29], v[204:205], v[156:157]
	v_mov_b64_e32 v[176:177], v[148:149]
	s_and_b64 vcc, exec, s[40:41]
	s_cbranch_vccz .LBB0_513
	s_branch .LBB0_514
.LBB0_603:
	v_mov_b32_e32 v174, v204
	v_mov_b32_e32 v175, v204
	v_mov_b32_e32 v172, v196
	v_mov_b32_e32 v173, v196
	v_pk_mul_f32 v[164:165], v[54:55], v[174:175]
	v_pk_mul_f32 v[168:169], v[52:53], v[204:205]
	s_waitcnt vmcnt(2)
	v_pk_fma_f32 v[166:167], v[172:173], v[154:155], v[164:165]
	v_pk_fma_f32 v[164:165], v[196:197], v[152:153], v[168:169]
	v_pk_mul_f32 v[168:169], v[26:27], v[174:175]
	v_pk_mul_f32 v[218:219], v[24:25], v[204:205]
	v_pk_fma_f32 v[170:171], v[172:173], v[162:163], v[168:169]
	v_pk_fma_f32 v[168:169], v[196:197], v[160:161], v[218:219]
	v_pk_mul_f32 v[174:175], v[22:23], v[174:175]
	v_pk_mul_f32 v[218:219], v[20:21], v[204:205]
	v_pk_mul_f32 v[178:179], v[172:173], v[150:151]
	v_pk_mul_f32 v[176:177], v[196:197], v[148:149]
	v_pk_fma_f32 v[174:175], v[172:173], v[158:159], v[174:175]
	v_pk_fma_f32 v[172:173], v[196:197], v[156:157], v[218:219]
	s_cbranch_execnz .LBB0_532
.LBB0_604:
	v_mov_b32_e32 v172, v204
	v_mov_b32_e32 v173, v204
	s_waitcnt vmcnt(2)
	v_mov_b64_e32 v[178:179], v[150:151]
	v_pk_fma_f32 v[166:167], v[54:55], v[172:173], v[154:155]
	v_pk_fma_f32 v[164:165], v[52:53], v[204:205], v[152:153]
	v_pk_fma_f32 v[170:171], v[26:27], v[172:173], v[162:163]
	v_pk_fma_f32 v[168:169], v[24:25], v[204:205], v[160:161]
	v_pk_fma_f32 v[174:175], v[22:23], v[172:173], v[158:159]
	v_pk_fma_f32 v[172:173], v[20:21], v[204:205], v[156:157]
	v_mov_b64_e32 v[176:177], v[148:149]
	s_and_b64 vcc, exec, s[40:41]
	s_cbranch_vccz .LBB0_533
	s_branch .LBB0_534
.LBB0_605:
	v_mov_b32_e32 v174, v204
	v_mov_b32_e32 v175, v204
	v_mov_b32_e32 v172, v196
	v_mov_b32_e32 v173, v196
	v_pk_mul_f32 v[164:165], v[46:47], v[174:175]
	v_pk_mul_f32 v[168:169], v[44:45], v[204:205]
	s_waitcnt vmcnt(2)
	v_pk_fma_f32 v[166:167], v[172:173], v[154:155], v[164:165]
	v_pk_fma_f32 v[164:165], v[196:197], v[152:153], v[168:169]
	v_pk_mul_f32 v[168:169], v[18:19], v[174:175]
	v_pk_mul_f32 v[218:219], v[16:17], v[204:205]
	v_pk_fma_f32 v[170:171], v[172:173], v[162:163], v[168:169]
	v_pk_fma_f32 v[168:169], v[196:197], v[160:161], v[218:219]
	v_pk_mul_f32 v[174:175], v[12:13], v[174:175]
	v_pk_mul_f32 v[218:219], v[10:11], v[204:205]
	v_pk_mul_f32 v[178:179], v[172:173], v[150:151]
	v_pk_mul_f32 v[176:177], v[196:197], v[148:149]
	v_pk_fma_f32 v[174:175], v[172:173], v[158:159], v[174:175]
	v_pk_fma_f32 v[172:173], v[196:197], v[156:157], v[218:219]
	s_cbranch_execnz .LBB0_552
.LBB0_606:
	v_mov_b32_e32 v172, v204
	v_mov_b32_e32 v173, v204
	s_waitcnt vmcnt(2)
	v_mov_b64_e32 v[178:179], v[150:151]
	v_pk_fma_f32 v[166:167], v[46:47], v[172:173], v[154:155]
	v_pk_fma_f32 v[164:165], v[44:45], v[204:205], v[152:153]
	v_pk_fma_f32 v[170:171], v[18:19], v[172:173], v[162:163]
	v_pk_fma_f32 v[168:169], v[16:17], v[204:205], v[160:161]
	v_pk_fma_f32 v[174:175], v[12:13], v[172:173], v[158:159]
	v_pk_fma_f32 v[172:173], v[10:11], v[204:205], v[156:157]
	v_mov_b64_e32 v[176:177], v[148:149]
	s_and_b64 vcc, exec, s[40:41]
	s_cbranch_vccz .LBB0_553
	s_branch .LBB0_554
